# lora_in_rows: previous/next token rows loaded together with the current row (one wait per row instead of two chained)
# baseline (speedup 1.0000x reference)
; __device__ __forceinline__ void lora_in_rows(CArgs& a, int l, int gw, int ngw, int lane) {
;     ...
;     for (int row = gw; row < M; row += ngw) {
;         int t, Tn; if (row < ML) { t = row & 2047; Tn = 2048; } else { t = (row - ML) & 255; Tn = 256; }
;         const bool hp = t > 0, hn = t < Tn - 1;
;         if (lane < 52) {
;             const bf16_t* p = RW + (size_t)row * RWP + 3072 + 8 * lane;
;             f32x4 x0, x1, p0 = {0.f, 0.f, 0.f, 0.f}, p1 = p0, n0 = p0, n1 = p0;
;             unpack8(*(const u32x4*)p, x0, x1);
;             if (hp) unpack8(*(const u32x4*)(p - RWP), p0, p1);
;             if (hn) unpack8(*(const u32x4*)(p + RWP), n0, n1);
.LBB0_466:
	s_andn2_saveexec_b64 s[56:57], s[4:5]
	s_cbranch_execz .LBB0_463
	v_lshl_add_u64 v[24:25], s[54:55], 0, v[0:1]
	v_add_co_u32_e32 v10, vcc, 0x11201000, v24
	s_cmpk_lt_i32 s1, 0x4000
	s_nop 0
	v_addc_co_u32_e32 v11, vcc, 0, v25, vcc
	global_load_dwordx4 v[10:13], v[10:11], off offset:2048
	s_movk_i32 s3, 0x7ff
	s_cselect_b32 s3, s3, 0xff
	s_and_b32 s4, s3, s1
	s_cmp_eq_u32 s4, 0
	v_mov_b32_e32 v18, 0
	v_mov_b32_e32 v20, 0
	v_mov_b32_e32 v21, 0
	v_mov_b32_e32 v22, 0
	v_mov_b32_e32 v23, 0
	v_mov_b32_e32 v14, 0
	v_mov_b32_e32 v15, 0
	v_mov_b32_e32 v16, 0
	v_mov_b32_e32 v17, 0
	v_mov_b32_e32 v19, 0
	v_mov_b32_e32 v26, 0
	v_mov_b32_e32 v27, 0
	v_mov_b32_e32 v28, 0
	v_mov_b32_e32 v29, 0
	v_mov_b32_e32 v30, 0
	v_mov_b32_e32 v31, 0
	s_cbranch_scc1 .Lli_ld_next
	v_add_co_u32_e32 v14, vcc, 0x111ff000, v24
	s_nop 1
	v_addc_co_u32_e32 v15, vcc, 0, v25, vcc
	global_load_dwordx4 v[20:23], v[14:15], off offset:3072
.Lli_ld_next:
	s_cmp_eq_u32 s4, s3
	s_cbranch_scc1 .Lli_wait
	v_add_co_u32_e32 v18, vcc, 0x11203000, v24
	s_nop 1
	v_addc_co_u32_e32 v19, vcc, 0, v25, vcc
	global_load_dwordx4 v[24:27], v[18:19], off offset:1024
.Lli_wait:
	s_waitcnt vmcnt(0)
	s_cmp_eq_u32 s4, 0
	s_cbranch_scc1 .Lli_up_next
	v_lshlrev_b32_e32 v14, 16, v20
	v_and_b32_e32 v15, 0xffff0000, v20
	v_lshlrev_b32_e32 v16, 16, v21
	v_and_b32_e32 v17, 0xffff0000, v21
	v_lshlrev_b32_e32 v20, 16, v22
	v_and_b32_e32 v21, 0xffff0000, v22
	v_lshlrev_b32_e32 v22, 16, v23
	v_and_b32_e32 v23, 0xffff0000, v23
.Lli_up_next:
	s_cmp_eq_u32 s4, s3
	s_cbranch_scc1 .LBB0_471
	v_lshlrev_b32_e32 v28, 16, v24
	v_and_b32_e32 v29, 0xffff0000, v24
	v_lshlrev_b32_e32 v30, 16, v25
	v_and_b32_e32 v31, 0xffff0000, v25
	v_lshlrev_b32_e32 v18, 16, v26
	v_and_b32_e32 v19, 0xffff0000, v26
	v_lshlrev_b32_e32 v26, 16, v27
	v_and_b32_e32 v27, 0xffff0000, v27
